# HGRN pass 3: the 8 first-stage gate loads before the chunk loop issued together with one wait instead of 4 serial round trips
# baseline (speedup 1.0000x reference)
; #define HLOADS(g0_) do { _Pragma("unroll") for (int tp = 0; tp < 16; ++tp) { const size_t rb = (size_t)HROW((g0_) + pj * 16 + tp) * 4096; zr[tp] = zb[rb]; if (PASS == 3) qr[tp] = qb[rb]; } \
;             _Pragma("unroll") for (int s8 = 0; s8 < 8; ++s8) vv[s8] = vb[(size_t)HROW((g0_) + pj * 16 + vsh * 8 + s8) * 4096]; } while (0)
; template <int PASS>
; DEV void hgrn_task(unsigned char* lds, int task, int l, const bf16_t* BZ, float* E, float* Dd, float* OF, bf16_t* YB, const float* b_lb, const float* gout) {
;     ...
;         const bf16_t* zb = BZ + (dir ? 2048 : 1024) + h * 128 + pc; const bf16_t* qb = BZ + h * 128 + pc; const bf16_t* vb = BZ + 3072 + h * 64 + vn;
;         unsigned short zr[16], qr[16], vv[8];
;     ...
;         HLOADS(0);
;     ...
;                 u32x4 vw; vw.x = vv[0] | ((unsigned)vv[1] << 16); vw.y = vv[2] | ((unsigned)vv[3] << 16); vw.z = vv[4] | ((unsigned)vv[5] << 16); vw.w = vv[6] | ((unsigned)vv[7] << 16);
.LBB0_568:
	s_and_b64 s[4:5], s[28:29], exec
	v_cndmask_b32_e64 v34, v156, v150, s[28:29]
	s_cselect_b32 s34, 0x800, s62
	s_mov_b32 s35, 0
	v_ashrrev_i32_e32 v35, 31, v34
	v_lshl_add_u64 v[106:107], v[54:55], 0, s[34:35]
	v_lshlrev_b64 v[34:35], 13, v[34:35]
	v_lshl_add_u64 v[36:37], v[106:107], 0, v[34:35]
	v_lshl_add_u64 v[34:35], v[54:55], 0, v[34:35]
	flat_load_ushort v69, v[36:37]
	flat_load_ushort v71, v[34:35]
	v_cndmask_b32_e64 v34, v157, v158, s[28:29]
	v_ashrrev_i32_e32 v35, 31, v34
	v_lshlrev_b64 v[34:35], 13, v[34:35]
	v_lshl_add_u64 v[36:37], v[106:107], 0, v[34:35]
	v_lshl_add_u64 v[34:35], v[54:55], 0, v[34:35]
	flat_load_ushort v73, v[36:37]
	flat_load_ushort v75, v[34:35]
	v_cndmask_b32_e64 v34, v159, v160, s[28:29]
	v_ashrrev_i32_e32 v35, 31, v34
	v_lshlrev_b64 v[34:35], 13, v[34:35]
	v_lshl_add_u64 v[36:37], v[106:107], 0, v[34:35]
	v_lshl_add_u64 v[34:35], v[54:55], 0, v[34:35]
	flat_load_ushort v77, v[36:37]
	flat_load_ushort v79, v[34:35]
	v_cndmask_b32_e64 v34, v161, v162, s[28:29]
	v_ashrrev_i32_e32 v35, 31, v34
	v_lshlrev_b64 v[34:35], 13, v[34:35]
	v_lshl_add_u64 v[36:37], v[106:107], 0, v[34:35]
	v_lshl_add_u64 v[34:35], v[54:55], 0, v[34:35]
	flat_load_ushort v81, v[36:37]
	flat_load_ushort v83, v[34:35]
	v_cndmask_b32_e64 v34, v163, v164, s[28:29]
	v_ashrrev_i32_e32 v35, 31, v34
	v_lshlrev_b64 v[34:35], 13, v[34:35]
	v_lshl_add_u64 v[36:37], v[106:107], 0, v[34:35]
	v_lshl_add_u64 v[34:35], v[54:55], 0, v[34:35]
	flat_load_ushort v85, v[36:37]
	flat_load_ushort v87, v[34:35]
	v_cndmask_b32_e64 v34, v165, v166, s[28:29]
	v_ashrrev_i32_e32 v35, 31, v34
	v_lshlrev_b64 v[34:35], 13, v[34:35]
	v_lshl_add_u64 v[36:37], v[106:107], 0, v[34:35]
	v_lshl_add_u64 v[34:35], v[54:55], 0, v[34:35]
	flat_load_ushort v89, v[36:37]
	flat_load_ushort v91, v[34:35]
	v_cndmask_b32_e64 v34, v167, v168, s[28:29]
	v_ashrrev_i32_e32 v35, 31, v34
	v_lshlrev_b64 v[34:35], 13, v[34:35]
	v_lshl_add_u64 v[36:37], v[106:107], 0, v[34:35]
	v_lshl_add_u64 v[34:35], v[54:55], 0, v[34:35]
	flat_load_ushort v93, v[36:37]
	flat_load_ushort v95, v[34:35]
	v_cndmask_b32_e64 v34, v169, v170, s[28:29]
	v_ashrrev_i32_e32 v35, 31, v34
	v_lshlrev_b64 v[34:35], 13, v[34:35]
	v_lshl_add_u64 v[36:37], v[106:107], 0, v[34:35]
	v_lshl_add_u64 v[34:35], v[54:55], 0, v[34:35]
	flat_load_ushort v97, v[36:37]
	flat_load_ushort v99, v[34:35]
	v_cndmask_b32_e64 v34, v171, v172, s[28:29]
	v_ashrrev_i32_e32 v35, 31, v34
	v_lshlrev_b64 v[34:35], 13, v[34:35]
	v_lshl_add_u64 v[36:37], v[106:107], 0, v[34:35]
	v_lshl_add_u64 v[34:35], v[54:55], 0, v[34:35]
	flat_load_ushort v101, v[36:37]
	flat_load_ushort v243, v[34:35]
	v_cndmask_b32_e64 v34, v173, v174, s[28:29]
	v_ashrrev_i32_e32 v35, 31, v34
	v_lshlrev_b64 v[34:35], 13, v[34:35]
	v_lshl_add_u64 v[36:37], v[106:107], 0, v[34:35]
	v_lshl_add_u64 v[34:35], v[54:55], 0, v[34:35]
	flat_load_ushort v244, v[36:37]
	flat_load_ushort v245, v[34:35]
	v_cndmask_b32_e64 v34, v175, v176, s[28:29]
	v_ashrrev_i32_e32 v35, 31, v34
	v_lshlrev_b64 v[34:35], 13, v[34:35]
	v_lshl_add_u64 v[36:37], v[106:107], 0, v[34:35]
	v_lshl_add_u64 v[34:35], v[54:55], 0, v[34:35]
	flat_load_ushort v246, v[36:37]
	flat_load_ushort v247, v[34:35]
	v_cndmask_b32_e64 v34, v177, v178, s[28:29]
	v_ashrrev_i32_e32 v35, 31, v34
	v_lshlrev_b64 v[34:35], 13, v[34:35]
	v_lshl_add_u64 v[36:37], v[106:107], 0, v[34:35]
	v_lshl_add_u64 v[34:35], v[54:55], 0, v[34:35]
	flat_load_ushort v248, v[36:37]
	flat_load_ushort v250, v[34:35]
	v_cndmask_b32_e64 v34, v179, v180, s[28:29]
	v_ashrrev_i32_e32 v35, 31, v34
	v_lshlrev_b64 v[34:35], 13, v[34:35]
	v_lshl_add_u64 v[36:37], v[106:107], 0, v[34:35]
	v_lshl_add_u64 v[34:35], v[54:55], 0, v[34:35]
	flat_load_ushort v251, v[36:37]
	flat_load_ushort v252, v[34:35]
	v_cndmask_b32_e64 v34, v181, v182, s[28:29]
	v_ashrrev_i32_e32 v35, 31, v34
	v_lshlrev_b64 v[34:35], 13, v[34:35]
	v_lshl_add_u64 v[36:37], v[106:107], 0, v[34:35]
	v_lshl_add_u64 v[34:35], v[54:55], 0, v[34:35]
	flat_load_ushort v253, v[36:37]
	flat_load_ushort v194, v[34:35]
	v_cndmask_b32_e64 v34, v183, v184, s[28:29]
	v_ashrrev_i32_e32 v35, 31, v34
	v_lshlrev_b64 v[34:35], 13, v[34:35]
	v_lshl_add_u64 v[36:37], v[106:107], 0, v[34:35]
	v_lshl_add_u64 v[34:35], v[54:55], 0, v[34:35]
	flat_load_ushort v195, v[36:37]
	flat_load_ushort v196, v[34:35]
	v_cndmask_b32_e64 v34, v185, v186, s[28:29]
	v_ashrrev_i32_e32 v35, 31, v34
	v_lshlrev_b64 v[34:35], 13, v[34:35]
	v_lshl_add_u64 v[36:37], v[106:107], 0, v[34:35]
	v_lshl_add_u64 v[34:35], v[54:55], 0, v[34:35]
	flat_load_ushort v197, v[36:37]
	flat_load_ushort v198, v[34:35]
	v_cndmask_b32_e64 v38, v187, v151, s[28:29]
	v_ashrrev_i32_e32 v39, 31, v38
	v_lshlrev_b64 v[38:39], 13, v[38:39]
	v_lshl_add_u64 v[38:39], v[56:57], 0, v[38:39]
	flat_load_ushort v34, v[38:39]
	v_cndmask_b32_e64 v38, v188, v189, s[28:29]
	v_ashrrev_i32_e32 v39, 31, v38
	v_lshlrev_b64 v[38:39], 13, v[38:39]
	v_lshl_add_u64 v[38:39], v[56:57], 0, v[38:39]
	flat_load_ushort v53, v[38:39]
	v_cndmask_b32_e64 v38, v190, v191, s[28:29]
	v_ashrrev_i32_e32 v39, 31, v38
	v_lshlrev_b64 v[38:39], 13, v[38:39]
	v_lshl_add_u64 v[38:39], v[56:57], 0, v[38:39]
	flat_load_ushort v35, v[38:39]
	v_cndmask_b32_e64 v38, v192, v193, s[28:29]
	v_ashrrev_i32_e32 v39, 31, v38
	v_lshlrev_b64 v[38:39], 13, v[38:39]
	v_lshl_add_u64 v[38:39], v[56:57], 0, v[38:39]
	flat_load_ushort v103, v[38:39]
	v_cndmask_b32_e64 v38, v206, v207, s[28:29]
	v_ashrrev_i32_e32 v39, 31, v38
	v_lshlrev_b64 v[38:39], 13, v[38:39]
	v_lshl_add_u64 v[38:39], v[56:57], 0, v[38:39]
	flat_load_ushort v36, v[38:39]
	v_cndmask_b32_e64 v38, v208, v209, s[28:29]
	v_ashrrev_i32_e32 v39, 31, v38
	v_lshlrev_b64 v[38:39], 13, v[38:39]
	v_lshl_add_u64 v[38:39], v[56:57], 0, v[38:39]
	flat_load_ushort v104, v[38:39]
	v_cndmask_b32_e64 v38, v210, v211, s[28:29]
	v_ashrrev_i32_e32 v39, 31, v38
	v_lshlrev_b64 v[38:39], 13, v[38:39]
	v_lshl_add_u64 v[38:39], v[56:57], 0, v[38:39]
	flat_load_ushort v37, v[38:39]
	v_cndmask_b32_e64 v38, v212, v213, s[28:29]
	v_ashrrev_i32_e32 v39, 31, v38
	v_lshlrev_b64 v[38:39], 13, v[38:39]
	v_lshl_add_u64 v[38:39], v[56:57], 0, v[38:39]
	flat_load_ushort v108, v[38:39]
	v_sub_f32_e32 v109, 1.0, v105
	v_mov_b32_e32 v110, v105
	v_mov_b32_e32 v111, v105
	v_mov_b32_e32 v112, v109
	v_mov_b32_e32 v113, v109
	s_waitcnt vmcnt(0) lgkmcnt(0)
	v_lshl_or_b32 v34, v53, 16, v34
	v_lshl_or_b32 v35, v103, 16, v35
	v_lshl_or_b32 v36, v104, 16, v36
	v_lshl_or_b32 v37, v108, 16, v37
	v_cndmask_b32_e64 v38, v148, v145, s[28:29]
	v_lshlrev_b32_e32 v38, 8, v38
	v_add_u32_e32 v249, v154, v38
	s_branch .LBB0_570
